# per-tile s_sleep stagger replaced by a one-time half-period offset (blockIdx bit 3) at the four GEMM phase starts, on top of the pipelined epilogues
# speedup vs baseline: 1.0027x; 1.0027x over previous
; __global__ void __launch_bounds__(NTHREADS, 2) mega_kernel(Params p) {
;     ...
;         for (int rep = 0; rep < REP_GEMM; ++rep) {
;             EpiIn epi;
;             epi.P = (bf16_t*)(p.ws + OFF_P); epi.VTA = (bf16_t*)(p.ws + OFF_VTA); epi.VTC = (bf16_t*)(p.ws + OFF_VTC);
;             epi.FT = (bf16_t*)(p.ws + OFF_FT); epi.G = (float*)(p.ws + OFF_G);
;             const int nbx = (int)(gridDim.x >> 3), xg = bid & 7, jb = bid >> 3;
;             constexpr int TOT = (NTOK / 256) * 23, PERX = TOT / 8;
;             const int nround = PERX / nbx, nrem = PERX - nround * nbx;
;             auto tile_of = [&](int idx, int& tm, int& tn) {
;                 const int g = xg * PERX + idx, rg = g / 184; int r = g - rg * 184;
;                 if (r < 128) { tm = rg * 8 + ((r & 63) >> 3); tn = (r >> 6) * 8 + (r & 7); }
;                 else { r -= 128; tm = rg * 8 + r / 7; tn = 16 + r % 7; }
;             };
;             const bf16_t* Wl = WinT + (size_t)l * NPAD * 1024;
;             bool pref = false;
;             for (int rd = 0; rd < nround; ++rd) {
;                 int mt, nt, mt2 = 0, nt2 = 0;
;                 tile_of(rd * nbx + jb, mt, nt);
;                 const bool have2 = (rd + 1 < nround);
;                 if (have2) tile_of((rd + 1) * nbx + jb, mt2, nt2);
;                 if (nt >= 14 && nt < 22) gemm_tile_ring<8, false>(HM, 1024, Wl, 1024, 1024, mt * 256, nt * 128, lds, epi, pref, have2, mt2 * 256, nt2 * 128);
;                 else gemm_tile_ring<8, true>(HM, 1024, Wl, 1024, 1024, mt * 256, nt * 128, lds, epi, pref, have2, mt2 * 256, nt2 * 128);
;                 pref = have2;
;             }
.LBB0_250:
	s_or_b64 exec, exec, s[0:1]
	s_mul_i32 s18, s52, 0x2e0000
	v_readlane_b32 s4, v248, 47
	s_lshl_b64 s[0:1], s[18:19], 1
	v_readlane_b32 s8, v248, 51
	v_readlane_b32 s9, v248, 52
	s_add_u32 s2, s8, s0
	s_addc_u32 s3, s9, s1
	v_readlane_b32 s0, v250, 48
	v_readlane_b32 s1, v250, 49
	s_andn2_b64 vcc, exec, s[0:1]
	s_mul_hi_u32 s34, s52, 0x5c0000
	s_mul_i32 s35, s52, 0x5c0000
	s_waitcnt lgkmcnt(0)
	s_barrier
	s_cselect_b32 s99, 1, 0
	v_readlane_b32 s98, v248, 0
	s_nop 3
	s_bitcmp1_b32 s98, 3
	s_cbranch_scc0 .Lphstag_skip_B
	s_sleep 27

; __device__ __forceinline__ f32x4 mfma16(bf16x8 a, bf16x8 b, f32x4 c) { return __builtin_amdgcn_mfma_f32_16x16x32_bf16(a, b, c, 0, 0, 0); }
; template <int MI, bool SWAP, class Epi> ...
;     ...
;     for (int kt = 0; kt < nk; ++kt) {
;         if (kt + 1 < nk && !(prefetched && kt == 0)) { if (MI == 8) asm volatile("s_waitcnt vmcnt(6)\n\ts_barrier" ::: "memory"); else if (MI == 4) asm volatile("s_waitcnt vmcnt(4)\n\ts_barrier" ::: "memory"); else asm volatile("s_waitcnt vmcnt(3)\n\ts_barrier" ::: "memory"); }
;         else asm volatile("s_waitcnt vmcnt(0)\n\ts_barrier" ::: "memory");
;         if (kt + 2 < nk) { const int nx = (cur == 0) ? 2 : cur - 1; RING_STAGE(nx, (kt + 2) * 32); }
;         const int so = cur * STAGEB;
;         bf16x8 bf[4], af[MI];
; #pragma unroll
;         for (int j = 0; j < 4; ++j) bf[j] = *(const bf16x8*)(brdb + so + j * 1024);
; #pragma unroll
;         for (int i = 0; i < MI; ++i) af[i] = *(const bf16x8*)(ardb + so + i * 1024);
;         if (blockIdx.x & 256) __builtin_amdgcn_s_setprio(2); else __builtin_amdgcn_s_setprio(1);
; #pragma unroll
;         for (int i = 0; i < MI; ++i) {
; #pragma unroll
;             for (int j = 0; j < 4; ++j) {
;                 if (SWAP) acc[i][j] = mfma16(bf[j], af[i], acc[i][j]);
;                 else acc[i][j] = mfma16(af[i], bf[j], acc[i][j]);
;             }
;         }
;         __builtin_amdgcn_s_setprio(0);
;         cur = (cur == 2) ? 0 : cur + 1;
;     }
.LBB0_274:
	s_mul_i32 s8, s25, 0x6000
	s_add_i32 s9, s8, 0xffffa000
	s_cmp_lg_u32 s25, 0
	s_cselect_b32 s9, s9, 0xc000
	s_waitcnt vmcnt(6)
	s_barrier
	v_lshl_add_u64 v[128:129], v[178:179], 0, s[6:7]
	s_add_i32 s29, s9, s11
	s_mov_b32 s30, m0
	s_mov_b32 m0, s29
	s_nop 0
	global_load_lds_dwordx4 v[128:129], off
	s_mov_b32 m0, s30
	s_mov_b64 s[38:39], 0x8000
	v_lshl_add_u64 v[130:131], v[128:129], 0, s[38:39]
	s_add_i32 s30, s29, 0x400
	s_mov_b32 s31, m0
	s_mov_b32 m0, s30
	s_nop 0
	global_load_lds_dwordx4 v[130:131], off
	s_mov_b32 m0, s31
	s_mov_b64 s[30:31], 0x10000
	v_lshl_add_u64 v[130:131], v[128:129], 0, s[30:31]
	s_add_i32 s30, s29, 0x800
	s_mov_b32 s31, m0
	s_mov_b32 m0, s30
	s_nop 0
	global_load_lds_dwordx4 v[130:131], off
	s_mov_b32 m0, s31
	s_mov_b64 s[30:31], 0x18000
	v_lshl_add_u64 v[128:129], v[128:129], 0, s[30:31]
	s_addk_i32 s29, 0xc00
	s_mov_b32 s30, m0
	s_mov_b32 m0, s29
	s_nop 0
	global_load_lds_dwordx4 v[128:129], off
	s_mov_b32 m0, s30
	v_lshl_add_u64 v[128:129], v[176:177], 0, s[6:7]
	s_add_i32 s9, s9, s22
	s_mov_b32 s29, m0
	s_mov_b32 m0, s9
	s_nop 0
	global_load_lds_dwordx4 v[128:129], off
	s_mov_b32 m0, s29
	v_lshl_add_u64 v[128:129], v[128:129], 0, s[38:39]
	s_addk_i32 s9, 0x400
	s_mov_b32 s29, m0
	s_mov_b32 m0, s9
	s_nop 0
	global_load_lds_dwordx4 v[128:129], off
	s_mov_b32 m0, s29
	v_add_u32_e32 v140, s8, v223
	v_add_u32_e32 v144, s8, v222
	ds_read_b128 v[128:131], v140 offset:16384
	ds_read_b128 v[132:135], v140 offset:17408
	ds_read_b128 v[136:139], v140 offset:18432
	ds_read_b128 v[140:143], v140 offset:19456
	ds_read_b128 v[172:175], v144
	ds_read_b128 v[168:171], v144 offset:1024
	ds_read_b128 v[164:167], v144 offset:2048
	ds_read_b128 v[160:163], v144 offset:3072
	ds_read_b128 v[156:159], v144 offset:4096
	ds_read_b128 v[152:155], v144 offset:5120
	ds_read_b128 v[148:151], v144 offset:6144
	ds_read_b128 v[144:147], v144 offset:7168
	s_setprio 2
	s_waitcnt lgkmcnt(7)
	v_mfma_f32_16x16x32_bf16 v[124:127], v[128:131], v[172:175], v[124:127]
	v_mfma_f32_16x16x32_bf16 v[120:123], v[132:135], v[172:175], v[120:123]
	v_mfma_f32_16x16x32_bf16 v[116:119], v[136:139], v[172:175], v[116:119]
	v_mfma_f32_16x16x32_bf16 v[112:115], v[140:143], v[172:175], v[112:115]
	s_waitcnt lgkmcnt(6)
	v_mfma_f32_16x16x32_bf16 v[108:111], v[128:131], v[168:171], v[108:111]
	v_mfma_f32_16x16x32_bf16 v[104:107], v[132:135], v[168:171], v[104:107]
	v_mfma_f32_16x16x32_bf16 v[100:103], v[136:139], v[168:171], v[100:103]
	v_mfma_f32_16x16x32_bf16 v[96:99], v[140:143], v[168:171], v[96:99]
	s_waitcnt lgkmcnt(5)
	v_mfma_f32_16x16x32_bf16 v[92:95], v[128:131], v[164:167], v[92:95]
	v_mfma_f32_16x16x32_bf16 v[88:91], v[132:135], v[164:167], v[88:91]
	v_mfma_f32_16x16x32_bf16 v[84:87], v[136:139], v[164:167], v[84:87]
	v_mfma_f32_16x16x32_bf16 v[80:83], v[140:143], v[164:167], v[80:83]
	s_waitcnt lgkmcnt(4)
	v_mfma_f32_16x16x32_bf16 v[76:79], v[128:131], v[160:163], v[76:79]
	v_mfma_f32_16x16x32_bf16 v[72:75], v[132:135], v[160:163], v[72:75]
	v_mfma_f32_16x16x32_bf16 v[68:71], v[136:139], v[160:163], v[68:71]
	v_mfma_f32_16x16x32_bf16 v[64:67], v[140:143], v[160:163], v[64:67]
	s_waitcnt lgkmcnt(3)
	v_mfma_f32_16x16x32_bf16 v[60:63], v[128:131], v[156:159], v[60:63]
	v_mfma_f32_16x16x32_bf16 v[56:59], v[132:135], v[156:159], v[56:59]
	v_mfma_f32_16x16x32_bf16 v[52:55], v[136:139], v[156:159], v[52:55]
	v_mfma_f32_16x16x32_bf16 v[48:51], v[140:143], v[156:159], v[48:51]
	s_waitcnt lgkmcnt(2)
	v_mfma_f32_16x16x32_bf16 v[44:47], v[128:131], v[152:155], v[44:47]
	v_mfma_f32_16x16x32_bf16 v[40:43], v[132:135], v[152:155], v[40:43]
	v_mfma_f32_16x16x32_bf16 v[36:39], v[136:139], v[152:155], v[36:39]
	v_mfma_f32_16x16x32_bf16 v[32:35], v[140:143], v[152:155], v[32:35]
	s_waitcnt lgkmcnt(1)
	v_mfma_f32_16x16x32_bf16 v[28:31], v[128:131], v[148:151], v[28:31]
	v_mfma_f32_16x16x32_bf16 v[24:27], v[132:135], v[148:151], v[24:27]
	v_mfma_f32_16x16x32_bf16 v[20:23], v[136:139], v[148:151], v[20:23]
	v_mfma_f32_16x16x32_bf16 v[16:19], v[140:143], v[148:151], v[16:19]
	s_waitcnt lgkmcnt(0)
	v_mfma_f32_16x16x32_bf16 v[12:15], v[128:131], v[144:147], v[12:15]
	v_mfma_f32_16x16x32_bf16 v[8:11], v[132:135], v[144:147], v[8:11]
	v_mfma_f32_16x16x32_bf16 v[4:7], v[136:139], v[144:147], v[4:7]
	v_mfma_f32_16x16x32_bf16 v[0:3], v[140:143], v[144:147], v[0:3]
	s_setprio 0
	s_add_u32 s6, s6, 64
	s_addc_u32 s7, s7, 0

; __device__ __forceinline__ f32x4 mfma16(bf16x8 a, bf16x8 b, f32x4 c) { return __builtin_amdgcn_mfma_f32_16x16x32_bf16(a, b, c, 0, 0, 0); }
; template <int MI, bool SWAP, class Epi> ...
;     ...
;     for (int kt = 0; kt < nk; ++kt) {
;         if (kt + 1 < nk && !(prefetched && kt == 0)) { if (MI == 8) asm volatile("s_waitcnt vmcnt(6)\n\ts_barrier" ::: "memory"); else if (MI == 4) asm volatile("s_waitcnt vmcnt(4)\n\ts_barrier" ::: "memory"); else asm volatile("s_waitcnt vmcnt(3)\n\ts_barrier" ::: "memory"); }
;         else asm volatile("s_waitcnt vmcnt(0)\n\ts_barrier" ::: "memory");
;         if (kt + 2 < nk) { const int nx = (cur == 0) ? 2 : cur - 1; RING_STAGE(nx, (kt + 2) * 32); }
;         const int so = cur * STAGEB;
;         bf16x8 bf[4], af[MI];
; #pragma unroll
;         for (int j = 0; j < 4; ++j) bf[j] = *(const bf16x8*)(brdb + so + j * 1024);
; #pragma unroll
;         for (int i = 0; i < MI; ++i) af[i] = *(const bf16x8*)(ardb + so + i * 1024);
;         if (blockIdx.x & 256) __builtin_amdgcn_s_setprio(2); else __builtin_amdgcn_s_setprio(1);
; #pragma unroll
;         for (int i = 0; i < MI; ++i) {
; #pragma unroll
;             for (int j = 0; j < 4; ++j) {
;                 if (SWAP) acc[i][j] = mfma16(bf[j], af[i], acc[i][j]);
;                 else acc[i][j] = mfma16(af[i], bf[j], acc[i][j]);
;             }
;         }
;         __builtin_amdgcn_s_setprio(0);
;         cur = (cur == 2) ? 0 : cur + 1;
;     }
.LBB0_396:
	s_mul_i32 s6, s22, 0x6000
	s_add_i32 s7, s6, 0xffffa000
	s_cmp_lg_u32 s22, 0
	s_cselect_b32 s7, s7, 0xc000
	s_waitcnt vmcnt(6)
	s_barrier
	v_lshl_add_u64 v[128:129], v[178:179], 0, s[4:5]
	s_add_i32 s23, s7, s9
	s_mov_b32 s24, m0
	s_mov_b32 m0, s23
	s_nop 0
	global_load_lds_dwordx4 v[128:129], off
	s_mov_b32 m0, s24
	s_mov_b64 s[30:31], 0x8000
	v_lshl_add_u64 v[130:131], v[128:129], 0, s[30:31]
	s_add_i32 s24, s23, 0x400
	s_mov_b32 s25, m0
	s_mov_b32 m0, s24
	s_nop 0
	global_load_lds_dwordx4 v[130:131], off
	s_mov_b32 m0, s25
	s_mov_b64 s[24:25], 0x10000
	v_lshl_add_u64 v[130:131], v[128:129], 0, s[24:25]
	s_add_i32 s24, s23, 0x800
	s_mov_b32 s25, m0
	s_mov_b32 m0, s24
	s_nop 0
	global_load_lds_dwordx4 v[130:131], off
	s_mov_b32 m0, s25
	s_mov_b64 s[24:25], 0x18000
	v_lshl_add_u64 v[128:129], v[128:129], 0, s[24:25]
	s_addk_i32 s23, 0xc00
	s_mov_b32 s24, m0
	s_mov_b32 m0, s23
	s_nop 0
	global_load_lds_dwordx4 v[128:129], off
	s_mov_b32 m0, s24
	v_lshl_add_u64 v[128:129], v[176:177], 0, s[4:5]
	s_add_i32 s7, s7, s10
	s_mov_b32 s23, m0
	s_mov_b32 m0, s7
	s_nop 0
	global_load_lds_dwordx4 v[128:129], off
	s_mov_b32 m0, s23
	v_lshl_add_u64 v[128:129], v[128:129], 0, s[30:31]
	s_addk_i32 s7, 0x400
	s_mov_b32 s23, m0
	s_mov_b32 m0, s7
	s_nop 0
	global_load_lds_dwordx4 v[128:129], off
	s_mov_b32 m0, s23
	v_add_u32_e32 v140, s6, v223
	v_add_u32_e32 v144, s6, v222
	ds_read_b128 v[128:131], v140 offset:16384
	ds_read_b128 v[132:135], v140 offset:17408
	ds_read_b128 v[136:139], v140 offset:18432
	ds_read_b128 v[140:143], v140 offset:19456
	ds_read_b128 v[172:175], v144
	ds_read_b128 v[168:171], v144 offset:1024
	ds_read_b128 v[164:167], v144 offset:2048
	ds_read_b128 v[160:163], v144 offset:3072
	ds_read_b128 v[156:159], v144 offset:4096
	ds_read_b128 v[152:155], v144 offset:5120
	ds_read_b128 v[148:151], v144 offset:6144
	ds_read_b128 v[144:147], v144 offset:7168
	s_setprio 2
	s_waitcnt lgkmcnt(7)
	v_mfma_f32_16x16x32_bf16 v[124:127], v[172:175], v[128:131], v[124:127]
	v_mfma_f32_16x16x32_bf16 v[120:123], v[172:175], v[132:135], v[120:123]
	v_mfma_f32_16x16x32_bf16 v[116:119], v[172:175], v[136:139], v[116:119]
	v_mfma_f32_16x16x32_bf16 v[112:115], v[172:175], v[140:143], v[112:115]
	s_waitcnt lgkmcnt(6)
	v_mfma_f32_16x16x32_bf16 v[108:111], v[168:171], v[128:131], v[108:111]
	v_mfma_f32_16x16x32_bf16 v[104:107], v[168:171], v[132:135], v[104:107]
	v_mfma_f32_16x16x32_bf16 v[100:103], v[168:171], v[136:139], v[100:103]
	v_mfma_f32_16x16x32_bf16 v[96:99], v[168:171], v[140:143], v[96:99]
	s_waitcnt lgkmcnt(5)
	v_mfma_f32_16x16x32_bf16 v[92:95], v[164:167], v[128:131], v[92:95]
	v_mfma_f32_16x16x32_bf16 v[88:91], v[164:167], v[132:135], v[88:91]
	v_mfma_f32_16x16x32_bf16 v[84:87], v[164:167], v[136:139], v[84:87]
	v_mfma_f32_16x16x32_bf16 v[80:83], v[164:167], v[140:143], v[80:83]
	s_waitcnt lgkmcnt(4)
	v_mfma_f32_16x16x32_bf16 v[76:79], v[160:163], v[128:131], v[76:79]
	v_mfma_f32_16x16x32_bf16 v[72:75], v[160:163], v[132:135], v[72:75]
	v_mfma_f32_16x16x32_bf16 v[68:71], v[160:163], v[136:139], v[68:71]
	v_mfma_f32_16x16x32_bf16 v[64:67], v[160:163], v[140:143], v[64:67]
	s_waitcnt lgkmcnt(3)
	v_mfma_f32_16x16x32_bf16 v[60:63], v[156:159], v[128:131], v[60:63]
	v_mfma_f32_16x16x32_bf16 v[56:59], v[156:159], v[132:135], v[56:59]
	v_mfma_f32_16x16x32_bf16 v[52:55], v[156:159], v[136:139], v[52:55]
	v_mfma_f32_16x16x32_bf16 v[48:51], v[156:159], v[140:143], v[48:51]
	s_waitcnt lgkmcnt(2)
	v_mfma_f32_16x16x32_bf16 v[44:47], v[152:155], v[128:131], v[44:47]
	v_mfma_f32_16x16x32_bf16 v[40:43], v[152:155], v[132:135], v[40:43]
	v_mfma_f32_16x16x32_bf16 v[36:39], v[152:155], v[136:139], v[36:39]
	v_mfma_f32_16x16x32_bf16 v[32:35], v[152:155], v[140:143], v[32:35]
	s_waitcnt lgkmcnt(1)
	v_mfma_f32_16x16x32_bf16 v[28:31], v[148:151], v[128:131], v[28:31]
	v_mfma_f32_16x16x32_bf16 v[24:27], v[148:151], v[132:135], v[24:27]
	v_mfma_f32_16x16x32_bf16 v[20:23], v[148:151], v[136:139], v[20:23]
	v_mfma_f32_16x16x32_bf16 v[16:19], v[148:151], v[140:143], v[16:19]
	s_waitcnt lgkmcnt(0)
	v_mfma_f32_16x16x32_bf16 v[12:15], v[144:147], v[128:131], v[12:15]
	v_mfma_f32_16x16x32_bf16 v[8:11], v[144:147], v[132:135], v[8:11]
	v_mfma_f32_16x16x32_bf16 v[4:7], v[144:147], v[136:139], v[4:7]
	v_mfma_f32_16x16x32_bf16 v[0:3], v[144:147], v[140:143], v[0:3]
	s_setprio 0
	s_add_u32 s4, s4, 64
	s_addc_u32 s5, s5, 0

; __global__ void __launch_bounds__(NTHREADS, 2) mega_kernel(Params p) {
;     ...
;         const int Mrows = last ? NLAT : NTOK;
;         {
;             EpiRes epi; epi.srcLat = srcLat; epi.srcCtx = srcCtx; epi.dstLat = p.out; epi.dstCtx = ctxres;
;             epi.mod = modall + (size_t)l * 17 * 6144; epi.gidx = 2;
;             int it = 0, mt, nt; bool have = next_tile(it, NLAT / 256, 8, mt, nt), pref = false;
;             while (have) {
;                 int it2 = it + 1, mt2 = 0, nt2 = 0; const bool have2 = next_tile(it2, NLAT / 256, 8, mt2, nt2);
;                 gemm_tile_ring<8, true>(HM, 1024, WoutT + (size_t)l * 1024 * 1024, 1024, 1024, mt * 256, nt * 128, lds, epi, pref, have2, mt2 * 256, nt2 * 128);
;                 pref = have2; have = have2; it = it2; mt = mt2; nt = nt2;
;             }
.LBB0_1927:
	s_or_b64 exec, exec, s[0:1]
	v_readlane_b32 s0, v250, 55
	v_readlane_b32 s1, v250, 56
	s_andn2_b64 vcc, exec, s[0:1]
	s_waitcnt lgkmcnt(0)
	v_cndmask_b32_e64 v0, 0, 1, s[0:1]
	v_readlane_b32 s0, v250, 59
	v_cmp_ne_u32_e64 s[2:3], 1, v0
	v_readlane_b32 s1, v250, 60
	s_barrier
	s_cselect_b32 s99, 1, 0
	v_readlane_b32 s98, v248, 0
	s_nop 3
	s_bitcmp1_b32 s98, 3
	s_cbranch_scc0 .Lphstag_skip_G
	s_sleep 27

; __device__ __forceinline__ f32x4 mfma16(bf16x8 a, bf16x8 b, f32x4 c) { return __builtin_amdgcn_mfma_f32_16x16x32_bf16(a, b, c, 0, 0, 0); }
; template <int MI, bool SWAP, class Epi> ...
;     ...
;     for (int kt = 0; kt < nk; ++kt) {
;         if (kt + 1 < nk && !(prefetched && kt == 0)) { if (MI == 8) asm volatile("s_waitcnt vmcnt(6)\n\ts_barrier" ::: "memory"); else if (MI == 4) asm volatile("s_waitcnt vmcnt(4)\n\ts_barrier" ::: "memory"); else asm volatile("s_waitcnt vmcnt(3)\n\ts_barrier" ::: "memory"); }
;         else asm volatile("s_waitcnt vmcnt(0)\n\ts_barrier" ::: "memory");
;         if (kt + 2 < nk) { const int nx = (cur == 0) ? 2 : cur - 1; RING_STAGE(nx, (kt + 2) * 32); }
;         const int so = cur * STAGEB;
;         bf16x8 bf[4], af[MI];
; #pragma unroll
;         for (int j = 0; j < 4; ++j) bf[j] = *(const bf16x8*)(brdb + so + j * 1024);
; #pragma unroll
;         for (int i = 0; i < MI; ++i) af[i] = *(const bf16x8*)(ardb + so + i * 1024);
;         if (blockIdx.x & 256) __builtin_amdgcn_s_setprio(2); else __builtin_amdgcn_s_setprio(1);
; #pragma unroll
;         for (int i = 0; i < MI; ++i) {
; #pragma unroll
;             for (int j = 0; j < 4; ++j) {
;                 if (SWAP) acc[i][j] = mfma16(bf[j], af[i], acc[i][j]);
;                 else acc[i][j] = mfma16(af[i], bf[j], acc[i][j]);
;             }
;         }
;         __builtin_amdgcn_s_setprio(0);
;         cur = (cur == 2) ? 0 : cur + 1;
;     }
.LBB0_1976:
	s_mul_i32 s8, s28, 0x6000
	s_add_i32 s9, s8, 0xffffa000
	s_cmp_lg_u32 s28, 0
	s_cselect_b32 s9, s9, 0xc000
	s_waitcnt vmcnt(6)
	s_barrier
	v_lshl_add_u64 v[128:129], v[178:179], 0, s[6:7]
	s_add_i32 s29, s9, s24
	s_mov_b32 s30, m0
	s_mov_b32 m0, s29
	s_nop 0
	global_load_lds_dwordx4 v[128:129], off
	s_mov_b32 m0, s30
	s_mov_b64 s[34:35], 0x8000
	v_lshl_add_u64 v[130:131], v[128:129], 0, s[34:35]
	s_add_i32 s30, s29, 0x400
	s_mov_b32 s31, m0
	s_mov_b32 m0, s30
	s_nop 0
	global_load_lds_dwordx4 v[130:131], off
	s_mov_b32 m0, s31
	s_mov_b64 s[30:31], 0x10000
	v_lshl_add_u64 v[130:131], v[128:129], 0, s[30:31]
	s_add_i32 s30, s29, 0x800
	s_mov_b32 s31, m0
	s_mov_b32 m0, s30
	s_nop 0
	global_load_lds_dwordx4 v[130:131], off
	s_mov_b32 m0, s31
	s_mov_b64 s[30:31], 0x18000
	v_lshl_add_u64 v[128:129], v[128:129], 0, s[30:31]
	s_addk_i32 s29, 0xc00
	s_mov_b32 s30, m0
	s_mov_b32 m0, s29
	s_nop 0
	global_load_lds_dwordx4 v[128:129], off
	s_mov_b32 m0, s30
	v_lshl_add_u64 v[128:129], v[176:177], 0, s[6:7]
	s_add_i32 s9, s9, s25
	s_mov_b32 s29, m0
	s_mov_b32 m0, s9
	s_nop 0
	global_load_lds_dwordx4 v[128:129], off
	s_mov_b32 m0, s29
	v_lshl_add_u64 v[128:129], v[128:129], 0, s[34:35]
	s_addk_i32 s9, 0x400
	s_mov_b32 s29, m0
	s_mov_b32 m0, s9
	s_nop 0
	global_load_lds_dwordx4 v[128:129], off
	s_mov_b32 m0, s29
	v_add_u32_e32 v140, s8, v223
	v_add_u32_e32 v144, s8, v222
	ds_read_b128 v[128:131], v140 offset:16384
	ds_read_b128 v[132:135], v140 offset:17408
	ds_read_b128 v[136:139], v140 offset:18432
	ds_read_b128 v[140:143], v140 offset:19456
	ds_read_b128 v[172:175], v144
	ds_read_b128 v[168:171], v144 offset:1024
	ds_read_b128 v[164:167], v144 offset:2048
	ds_read_b128 v[160:163], v144 offset:3072
	ds_read_b128 v[156:159], v144 offset:4096
	ds_read_b128 v[152:155], v144 offset:5120
	ds_read_b128 v[148:151], v144 offset:6144
	ds_read_b128 v[144:147], v144 offset:7168
	s_setprio 2
	s_waitcnt lgkmcnt(7)
	v_mfma_f32_16x16x32_bf16 v[120:123], v[128:131], v[172:175], v[120:123]
	v_mfma_f32_16x16x32_bf16 v[116:119], v[132:135], v[172:175], v[116:119]
	v_mfma_f32_16x16x32_bf16 v[112:115], v[136:139], v[172:175], v[112:115]
	v_mfma_f32_16x16x32_bf16 v[108:111], v[140:143], v[172:175], v[108:111]
	s_waitcnt lgkmcnt(6)
	v_mfma_f32_16x16x32_bf16 v[104:107], v[128:131], v[168:171], v[104:107]
	v_mfma_f32_16x16x32_bf16 v[100:103], v[132:135], v[168:171], v[100:103]
	v_mfma_f32_16x16x32_bf16 v[96:99], v[136:139], v[168:171], v[96:99]
	v_mfma_f32_16x16x32_bf16 v[92:95], v[140:143], v[168:171], v[92:95]
	s_waitcnt lgkmcnt(5)
	v_mfma_f32_16x16x32_bf16 v[88:91], v[128:131], v[164:167], v[88:91]
	v_mfma_f32_16x16x32_bf16 v[84:87], v[132:135], v[164:167], v[84:87]
	v_mfma_f32_16x16x32_bf16 v[80:83], v[136:139], v[164:167], v[80:83]
	v_mfma_f32_16x16x32_bf16 v[76:79], v[140:143], v[164:167], v[76:79]
	s_waitcnt lgkmcnt(4)
	v_mfma_f32_16x16x32_bf16 v[72:75], v[128:131], v[160:163], v[72:75]
	v_mfma_f32_16x16x32_bf16 v[68:71], v[132:135], v[160:163], v[68:71]
	v_mfma_f32_16x16x32_bf16 v[64:67], v[136:139], v[160:163], v[64:67]
	v_mfma_f32_16x16x32_bf16 v[60:63], v[140:143], v[160:163], v[60:63]
	s_waitcnt lgkmcnt(3)
	v_mfma_f32_16x16x32_bf16 v[56:59], v[128:131], v[156:159], v[56:59]
	v_mfma_f32_16x16x32_bf16 v[52:55], v[132:135], v[156:159], v[52:55]
	v_mfma_f32_16x16x32_bf16 v[48:51], v[136:139], v[156:159], v[48:51]
	v_mfma_f32_16x16x32_bf16 v[44:47], v[140:143], v[156:159], v[44:47]
	s_waitcnt lgkmcnt(2)
	v_mfma_f32_16x16x32_bf16 v[40:43], v[128:131], v[152:155], v[40:43]
	v_mfma_f32_16x16x32_bf16 v[36:39], v[132:135], v[152:155], v[36:39]
	v_mfma_f32_16x16x32_bf16 v[32:35], v[136:139], v[152:155], v[32:35]
	v_mfma_f32_16x16x32_bf16 v[28:31], v[140:143], v[152:155], v[28:31]
	s_waitcnt lgkmcnt(1)
	v_mfma_f32_16x16x32_bf16 v[24:27], v[128:131], v[148:151], v[24:27]
	v_mfma_f32_16x16x32_bf16 v[20:23], v[132:135], v[148:151], v[20:23]
	v_mfma_f32_16x16x32_bf16 v[16:19], v[136:139], v[148:151], v[16:19]
	v_mfma_f32_16x16x32_bf16 v[12:15], v[140:143], v[148:151], v[12:15]
	s_waitcnt lgkmcnt(0)
	v_mfma_f32_16x16x32_bf16 v[8:11], v[128:131], v[144:147], v[8:11]
	v_mfma_f32_16x16x32_bf16 v[4:7], v[132:135], v[144:147], v[4:7]
	v_mfma_f32_16x16x32_bf16 v[0:3], v[136:139], v[144:147], v[0:3]
	v_mfma_f32_16x16x32_bf16 v[124:127], v[140:143], v[144:147], v[124:127]
	s_setprio 0
	s_add_u32 s6, s6, 64
	s_addc_u32 s7, s7, 0

; __device__ __forceinline__ bool tile_map(int it, int MT, int NT, int& mt, int& nt) {
;     const int xcd = blockIdx.x & 7, j = blockIdx.x >> 3, SR = (int)(gridDim.x >> 6);
;     const int ncg = (NT + 7) >> 3, nrg = (MT + SR - 1) / SR;
;     const int s = xcd + 8 * it;
;     if (s >= nrg * ncg) return false;
;     const int rg = s / ncg, cgi = s - rg * ncg;
;     mt = rg * SR + (j >> 3); nt = cgi * 8 + (j & 7);
;     return true;
; }
; __global__ void __launch_bounds__(NTHREADS, 2) mega_kernel(Params p) {
;     ...
;         for (int rep = 0; rep < REP_GEMM; ++rep) {
;             EpiFF1 epi; epi.HID = (bf16_t*)(p.ws + OFF_HID);
;             int it = 0, mt, nt; bool have = next_tile(it, Mrows / 256, 32, mt, nt), pref = false;
;             while (have) {
;                 int it2 = it + 1, mt2 = 0, nt2 = 0; const bool have2 = next_tile(it2, Mrows / 256, 32, mt2, nt2);
;                 gemm_tile_ring<8, true>(HM, 1024, W1T + (size_t)l * 4096 * 1024, 1024, 1024, mt * 256, nt * 128, lds, epi, pref, have2, mt2 * 256, nt2 * 128);
;                 pref = have2; have = have2; it = it2; mt = mt2; nt = nt2;
;             }
.LBB0_2143:
	v_writelane_b32 v253, s25, 46
	s_or_b64 exec, exec, s[0:1]
	s_lshr_b32 s18, s16, 8
	v_readlane_b32 s0, v250, 47
	s_add_i32 s0, s0, s18
	v_readlane_b32 s1, v251, 8
	s_mul_hi_u32 s1, s0, s1
	s_mul_i32 s2, s1, s56
	s_sub_i32 s0, s0, s2
	s_add_i32 s2, s1, 1
	s_sub_i32 s3, s0, s56
	s_cmp_ge_u32 s0, s56
	s_cselect_b32 s1, s2, s1
	s_cselect_b32 s0, s3, s0
	s_add_i32 s2, s1, 1
	s_cmp_ge_u32 s0, s56
	s_cselect_b32 s0, s2, s1
	s_lshl_b32 s33, s0, 2
	v_readlane_b32 s0, v250, 61
	v_writelane_b32 v252, s73, 36
	s_cmp_ge_u32 s0, s33
	v_writelane_b32 v252, s74, 39
	s_waitcnt lgkmcnt(0)
	s_barrier
	s_cselect_b32 s99, 1, 0
	v_readlane_b32 s98, v248, 0
	s_nop 3
	s_bitcmp1_b32 s98, 3
	s_cbranch_scc0 .Lphstag_skip_I
	s_sleep 27

; __device__ __forceinline__ f32x4 mfma16(bf16x8 a, bf16x8 b, f32x4 c) { return __builtin_amdgcn_mfma_f32_16x16x32_bf16(a, b, c, 0, 0, 0); }
; template <int MI, bool SWAP, class Epi> ...
;     ...
;     for (int kt = 0; kt < nk; ++kt) {
;         if (kt + 1 < nk && !(prefetched && kt == 0)) { if (MI == 8) asm volatile("s_waitcnt vmcnt(6)\n\ts_barrier" ::: "memory"); else if (MI == 4) asm volatile("s_waitcnt vmcnt(4)\n\ts_barrier" ::: "memory"); else asm volatile("s_waitcnt vmcnt(3)\n\ts_barrier" ::: "memory"); }
;         else asm volatile("s_waitcnt vmcnt(0)\n\ts_barrier" ::: "memory");
;         if (kt + 2 < nk) { const int nx = (cur == 0) ? 2 : cur - 1; RING_STAGE(nx, (kt + 2) * 32); }
;         const int so = cur * STAGEB;
;         bf16x8 bf[4], af[MI];
; #pragma unroll
;         for (int j = 0; j < 4; ++j) bf[j] = *(const bf16x8*)(brdb + so + j * 1024);
; #pragma unroll
;         for (int i = 0; i < MI; ++i) af[i] = *(const bf16x8*)(ardb + so + i * 1024);
;         if (blockIdx.x & 256) __builtin_amdgcn_s_setprio(2); else __builtin_amdgcn_s_setprio(1);
; #pragma unroll
;         for (int i = 0; i < MI; ++i) {
; #pragma unroll
;             for (int j = 0; j < 4; ++j) {
;                 if (SWAP) acc[i][j] = mfma16(bf[j], af[i], acc[i][j]);
;                 else acc[i][j] = mfma16(af[i], bf[j], acc[i][j]);
;             }
;         }
;         __builtin_amdgcn_s_setprio(0);
;         cur = (cur == 2) ? 0 : cur + 1;
;     }
.LBB0_2193:
	s_mul_i32 s8, s27, 0x6000
	s_add_i32 s9, s8, 0xffffa000
	s_cmp_lg_u32 s27, 0
	s_cselect_b32 s9, s9, 0xc000
	s_waitcnt vmcnt(6)
	s_barrier
	v_lshl_add_u64 v[128:129], v[178:179], 0, s[6:7]
	s_add_i32 s28, s9, s23
	s_mov_b32 s29, m0
	s_mov_b32 m0, s28
	s_nop 0
	global_load_lds_dwordx4 v[128:129], off
	s_mov_b32 m0, s29
	s_mov_b64 s[12:13], 0x8000
	v_lshl_add_u64 v[130:131], v[128:129], 0, s[12:13]
	s_add_i32 s29, s28, 0x400
	s_mov_b32 s30, m0
	s_mov_b32 m0, s29
	s_nop 0
	global_load_lds_dwordx4 v[130:131], off
	s_mov_b32 m0, s30
	s_mov_b64 s[14:15], 0x10000
	v_lshl_add_u64 v[130:131], v[128:129], 0, s[14:15]
	s_add_i32 s29, s28, 0x800
	s_mov_b32 s30, m0
	s_mov_b32 m0, s29
	s_nop 0
	global_load_lds_dwordx4 v[130:131], off
	s_mov_b32 m0, s30
	s_mov_b64 s[14:15], 0x18000
	v_lshl_add_u64 v[128:129], v[128:129], 0, s[14:15]
	s_addk_i32 s28, 0xc00
	s_mov_b32 s29, m0
	s_mov_b32 m0, s28
	s_nop 0
	global_load_lds_dwordx4 v[128:129], off
	s_mov_b32 m0, s29
	v_lshl_add_u64 v[128:129], v[176:177], 0, s[6:7]
	s_add_i32 s9, s9, s24
	s_mov_b32 s28, m0
	s_mov_b32 m0, s9
	s_nop 0
	global_load_lds_dwordx4 v[128:129], off
	s_mov_b32 m0, s28
	v_lshl_add_u64 v[128:129], v[128:129], 0, s[12:13]
	s_addk_i32 s9, 0x400
	s_mov_b32 s28, m0
	s_mov_b32 m0, s9
	s_nop 0
	global_load_lds_dwordx4 v[128:129], off
	s_mov_b32 m0, s28
	v_add_u32_e32 v140, s8, v223
	v_add_u32_e32 v144, s8, v222
	ds_read_b128 v[128:131], v140 offset:16384
	ds_read_b128 v[132:135], v140 offset:17408
	ds_read_b128 v[136:139], v140 offset:18432
	ds_read_b128 v[140:143], v140 offset:19456
	ds_read_b128 v[172:175], v144
	ds_read_b128 v[168:171], v144 offset:1024
	ds_read_b128 v[164:167], v144 offset:2048
	ds_read_b128 v[160:163], v144 offset:3072
	ds_read_b128 v[156:159], v144 offset:4096
	ds_read_b128 v[152:155], v144 offset:5120
	ds_read_b128 v[148:151], v144 offset:6144
	ds_read_b128 v[144:147], v144 offset:7168
	s_setprio 2
	s_waitcnt lgkmcnt(7)
	v_mfma_f32_16x16x32_bf16 v[120:123], v[128:131], v[172:175], v[120:123]
	v_mfma_f32_16x16x32_bf16 v[116:119], v[132:135], v[172:175], v[116:119]
	v_mfma_f32_16x16x32_bf16 v[112:115], v[136:139], v[172:175], v[112:115]
	v_mfma_f32_16x16x32_bf16 v[108:111], v[140:143], v[172:175], v[108:111]
	s_waitcnt lgkmcnt(6)
	v_mfma_f32_16x16x32_bf16 v[104:107], v[128:131], v[168:171], v[104:107]
	v_mfma_f32_16x16x32_bf16 v[100:103], v[132:135], v[168:171], v[100:103]
	v_mfma_f32_16x16x32_bf16 v[96:99], v[136:139], v[168:171], v[96:99]
	v_mfma_f32_16x16x32_bf16 v[92:95], v[140:143], v[168:171], v[92:95]
	s_waitcnt lgkmcnt(5)
	v_mfma_f32_16x16x32_bf16 v[88:91], v[128:131], v[164:167], v[88:91]
	v_mfma_f32_16x16x32_bf16 v[84:87], v[132:135], v[164:167], v[84:87]
	v_mfma_f32_16x16x32_bf16 v[80:83], v[136:139], v[164:167], v[80:83]
	v_mfma_f32_16x16x32_bf16 v[76:79], v[140:143], v[164:167], v[76:79]
	s_waitcnt lgkmcnt(4)
	v_mfma_f32_16x16x32_bf16 v[72:75], v[128:131], v[160:163], v[72:75]
	v_mfma_f32_16x16x32_bf16 v[68:71], v[132:135], v[160:163], v[68:71]
	v_mfma_f32_16x16x32_bf16 v[64:67], v[136:139], v[160:163], v[64:67]
	v_mfma_f32_16x16x32_bf16 v[60:63], v[140:143], v[160:163], v[60:63]
	s_waitcnt lgkmcnt(3)
	v_mfma_f32_16x16x32_bf16 v[56:59], v[128:131], v[156:159], v[56:59]
	v_mfma_f32_16x16x32_bf16 v[52:55], v[132:135], v[156:159], v[52:55]
	v_mfma_f32_16x16x32_bf16 v[48:51], v[136:139], v[156:159], v[48:51]
	v_mfma_f32_16x16x32_bf16 v[44:47], v[140:143], v[156:159], v[44:47]
	s_waitcnt lgkmcnt(2)
	v_mfma_f32_16x16x32_bf16 v[40:43], v[128:131], v[152:155], v[40:43]
	v_mfma_f32_16x16x32_bf16 v[36:39], v[132:135], v[152:155], v[36:39]
	v_mfma_f32_16x16x32_bf16 v[32:35], v[136:139], v[152:155], v[32:35]
	v_mfma_f32_16x16x32_bf16 v[28:31], v[140:143], v[152:155], v[28:31]
	s_waitcnt lgkmcnt(1)
	v_mfma_f32_16x16x32_bf16 v[24:27], v[128:131], v[148:151], v[24:27]
	v_mfma_f32_16x16x32_bf16 v[20:23], v[132:135], v[148:151], v[20:23]
	v_mfma_f32_16x16x32_bf16 v[16:19], v[136:139], v[148:151], v[16:19]
	v_mfma_f32_16x16x32_bf16 v[12:15], v[140:143], v[148:151], v[12:15]
	s_waitcnt lgkmcnt(0)
	v_mfma_f32_16x16x32_bf16 v[8:11], v[128:131], v[144:147], v[8:11]
	v_mfma_f32_16x16x32_bf16 v[4:7], v[132:135], v[144:147], v[4:7]
	v_mfma_f32_16x16x32_bf16 v[0:3], v[136:139], v[144:147], v[0:3]
	v_mfma_f32_16x16x32_bf16 v[124:127], v[140:143], v[144:147], v[124:127]
	s_setprio 0
	s_add_u32 s6, s6, 64
	s_addc_u32 s7, s7, 0

; __global__ void __launch_bounds__(NTHREADS, 2) mega_kernel(Params p) {
;     ...
;         {
;             EpiRes epi; epi.srcLat = p.out; epi.srcCtx = ctxres; epi.dstLat = p.out; epi.dstCtx = ctxres;
;             epi.mod = modall + (size_t)l * 17 * 6144; epi.gidx = 5;
;             int it = 0, mt, nt; bool have = next_tile(it, NLAT / 256, 8, mt, nt), pref = false;
;             while (have) {
;                 int it2 = it + 1, mt2 = 0, nt2 = 0; const bool have2 = next_tile(it2, NLAT / 256, 8, mt2, nt2);
;                 gemm_tile_ring<8, true>((const bf16_t*)(p.ws + OFF_HID), 4096, W2T + (size_t)l * 1024 * 4096, 4096, 4096, mt * 256, nt * 128, lds, epi, pref, have2, mt2 * 256, nt2 * 128);
;                 pref = have2; have = have2; it = it2; mt = mt2; nt = nt2;
;             }
.LBB0_2260:
	s_or_b64 exec, exec, s[0:1]
	v_readlane_b32 s0, v252, 34
	v_readlane_b32 s1, v252, 35
	s_and_b64 vcc, exec, s[0:1]
	s_waitcnt lgkmcnt(0)
	s_barrier
	s_cselect_b32 s99, 1, 0
	v_readlane_b32 s98, v248, 0
	s_nop 3
	s_bitcmp1_b32 s98, 3
	s_cbranch_scc0 .Lphstag_skip_J
	s_sleep 27

; __device__ __forceinline__ f32x4 mfma16(bf16x8 a, bf16x8 b, f32x4 c) { return __builtin_amdgcn_mfma_f32_16x16x32_bf16(a, b, c, 0, 0, 0); }
; template <int MI, bool SWAP, class Epi> ...
;     ...
;     for (int kt = 0; kt < nk; ++kt) {
;         if (kt + 1 < nk && !(prefetched && kt == 0)) { if (MI == 8) asm volatile("s_waitcnt vmcnt(6)\n\ts_barrier" ::: "memory"); else if (MI == 4) asm volatile("s_waitcnt vmcnt(4)\n\ts_barrier" ::: "memory"); else asm volatile("s_waitcnt vmcnt(3)\n\ts_barrier" ::: "memory"); }
;         else asm volatile("s_waitcnt vmcnt(0)\n\ts_barrier" ::: "memory");
;         if (kt + 2 < nk) { const int nx = (cur == 0) ? 2 : cur - 1; RING_STAGE(nx, (kt + 2) * 32); }
;         const int so = cur * STAGEB;
;         bf16x8 bf[4], af[MI];
; #pragma unroll
;         for (int j = 0; j < 4; ++j) bf[j] = *(const bf16x8*)(brdb + so + j * 1024);
; #pragma unroll
;         for (int i = 0; i < MI; ++i) af[i] = *(const bf16x8*)(ardb + so + i * 1024);
;         if (blockIdx.x & 256) __builtin_amdgcn_s_setprio(2); else __builtin_amdgcn_s_setprio(1);
; #pragma unroll
;         for (int i = 0; i < MI; ++i) {
; #pragma unroll
;             for (int j = 0; j < 4; ++j) {
;                 if (SWAP) acc[i][j] = mfma16(bf[j], af[i], acc[i][j]);
;                 else acc[i][j] = mfma16(af[i], bf[j], acc[i][j]);
;             }
;         }
;         __builtin_amdgcn_s_setprio(0);
;         cur = (cur == 2) ? 0 : cur + 1;
;     }
.LBB0_2308:
	s_mul_i32 s8, s30, 0x6000
	s_add_i32 s9, s8, 0xffffa000
	s_cmp_lg_u32 s30, 0
	s_cselect_b32 s9, s9, 0xc000
	s_waitcnt vmcnt(6)
	s_barrier
	v_lshl_add_u64 v[128:129], v[178:179], 0, s[6:7]
	s_add_i32 s31, s9, s26
	s_mov_b32 s34, m0
	s_mov_b32 m0, s31
	s_nop 0
	global_load_lds_dwordx4 v[128:129], off
	s_mov_b32 m0, s34
	s_mov_b64 s[12:13], 0x20000
	v_lshl_add_u64 v[130:131], v[128:129], 0, s[12:13]
	s_add_i32 s34, s31, 0x400
	s_mov_b32 s35, m0
	s_mov_b32 m0, s34
	s_nop 0
	global_load_lds_dwordx4 v[130:131], off
	s_mov_b32 m0, s35
	s_mov_b64 s[34:35], 0x40000
	v_lshl_add_u64 v[130:131], v[128:129], 0, s[34:35]
	s_add_i32 s34, s31, 0x800
	s_mov_b32 s35, m0
	s_mov_b32 m0, s34
	s_nop 0
	global_load_lds_dwordx4 v[130:131], off
	s_mov_b32 m0, s35
	s_mov_b64 s[34:35], 0x60000
	v_lshl_add_u64 v[128:129], v[128:129], 0, s[34:35]
	s_addk_i32 s31, 0xc00
	s_mov_b32 s34, m0
	s_mov_b32 m0, s31
	s_nop 0
	global_load_lds_dwordx4 v[128:129], off
	s_mov_b32 m0, s34
	v_lshl_add_u64 v[128:129], v[176:177], 0, s[6:7]
	s_add_i32 s9, s9, s27
	s_mov_b32 s31, m0
	s_mov_b32 m0, s9
	s_nop 0
	global_load_lds_dwordx4 v[128:129], off
	s_mov_b32 m0, s31
	v_lshl_add_u64 v[128:129], v[128:129], 0, s[12:13]
	s_addk_i32 s9, 0x400
	s_mov_b32 s31, m0
	s_mov_b32 m0, s9
	s_nop 0
	global_load_lds_dwordx4 v[128:129], off
	s_mov_b32 m0, s31
	v_add_u32_e32 v140, s8, v223
	v_add_u32_e32 v144, s8, v222
	ds_read_b128 v[128:131], v140 offset:16384
	ds_read_b128 v[132:135], v140 offset:17408
	ds_read_b128 v[136:139], v140 offset:18432
	ds_read_b128 v[140:143], v140 offset:19456
	ds_read_b128 v[172:175], v144
	ds_read_b128 v[168:171], v144 offset:1024
	ds_read_b128 v[164:167], v144 offset:2048
	ds_read_b128 v[160:163], v144 offset:3072
	ds_read_b128 v[156:159], v144 offset:4096
	ds_read_b128 v[152:155], v144 offset:5120
	ds_read_b128 v[148:151], v144 offset:6144
	ds_read_b128 v[144:147], v144 offset:7168
	s_setprio 2
	s_waitcnt lgkmcnt(7)
	v_mfma_f32_16x16x32_bf16 v[120:123], v[128:131], v[172:175], v[120:123]
	v_mfma_f32_16x16x32_bf16 v[116:119], v[132:135], v[172:175], v[116:119]
	v_mfma_f32_16x16x32_bf16 v[112:115], v[136:139], v[172:175], v[112:115]
	v_mfma_f32_16x16x32_bf16 v[108:111], v[140:143], v[172:175], v[108:111]
	s_waitcnt lgkmcnt(6)
	v_mfma_f32_16x16x32_bf16 v[104:107], v[128:131], v[168:171], v[104:107]
	v_mfma_f32_16x16x32_bf16 v[100:103], v[132:135], v[168:171], v[100:103]
	v_mfma_f32_16x16x32_bf16 v[96:99], v[136:139], v[168:171], v[96:99]
	v_mfma_f32_16x16x32_bf16 v[92:95], v[140:143], v[168:171], v[92:95]
	s_waitcnt lgkmcnt(5)
	v_mfma_f32_16x16x32_bf16 v[88:91], v[128:131], v[164:167], v[88:91]
	v_mfma_f32_16x16x32_bf16 v[84:87], v[132:135], v[164:167], v[84:87]
	v_mfma_f32_16x16x32_bf16 v[80:83], v[136:139], v[164:167], v[80:83]
	v_mfma_f32_16x16x32_bf16 v[76:79], v[140:143], v[164:167], v[76:79]
	s_waitcnt lgkmcnt(4)
	v_mfma_f32_16x16x32_bf16 v[72:75], v[128:131], v[160:163], v[72:75]
	v_mfma_f32_16x16x32_bf16 v[68:71], v[132:135], v[160:163], v[68:71]
	v_mfma_f32_16x16x32_bf16 v[64:67], v[136:139], v[160:163], v[64:67]
	v_mfma_f32_16x16x32_bf16 v[60:63], v[140:143], v[160:163], v[60:63]
	s_waitcnt lgkmcnt(3)
	v_mfma_f32_16x16x32_bf16 v[56:59], v[128:131], v[156:159], v[56:59]
	v_mfma_f32_16x16x32_bf16 v[52:55], v[132:135], v[156:159], v[52:55]
	v_mfma_f32_16x16x32_bf16 v[48:51], v[136:139], v[156:159], v[48:51]
	v_mfma_f32_16x16x32_bf16 v[44:47], v[140:143], v[156:159], v[44:47]
	s_waitcnt lgkmcnt(2)
	v_mfma_f32_16x16x32_bf16 v[40:43], v[128:131], v[152:155], v[40:43]
	v_mfma_f32_16x16x32_bf16 v[36:39], v[132:135], v[152:155], v[36:39]
	v_mfma_f32_16x16x32_bf16 v[32:35], v[136:139], v[152:155], v[32:35]
	v_mfma_f32_16x16x32_bf16 v[28:31], v[140:143], v[152:155], v[28:31]
	s_waitcnt lgkmcnt(1)
	v_mfma_f32_16x16x32_bf16 v[24:27], v[128:131], v[148:151], v[24:27]
	v_mfma_f32_16x16x32_bf16 v[20:23], v[132:135], v[148:151], v[20:23]
	v_mfma_f32_16x16x32_bf16 v[16:19], v[136:139], v[148:151], v[16:19]
	v_mfma_f32_16x16x32_bf16 v[12:15], v[140:143], v[148:151], v[12:15]
	s_waitcnt lgkmcnt(0)
	v_mfma_f32_16x16x32_bf16 v[8:11], v[128:131], v[144:147], v[8:11]
	v_mfma_f32_16x16x32_bf16 v[4:7], v[132:135], v[144:147], v[4:7]
	v_mfma_f32_16x16x32_bf16 v[0:3], v[136:139], v[144:147], v[0:3]
	v_mfma_f32_16x16x32_bf16 v[124:127], v[140:143], v[144:147], v[124:127]
	s_setprio 0
	s_add_u32 s6, s6, 64
	s_addc_u32 s7, s7, 0
